# scan: loop-invariant LDS addresses of stage Y and stage X hoisted out of the chunk loop into free VGPRs
# speedup vs baseline: 1.0167x; 1.0008x over previous
.LBB0_393:
	s_or_b64 exec, exec, s[74:75]
	s_lshl_b64 s[2:3], s[2:3], 24
	s_lshl_b64 s[2:3], s[2:3], 1
	v_readlane_b32 s19, v254, 44
	s_waitcnt lgkmcnt(0)
	s_barrier
	s_add_u32 s78, s19, s2
	v_readlane_b32 s2, v254, 45
	v_lshlrev_b32_e32 v189, 8, v18
	v_mov_b32_e32 v14, 0
	s_mov_b32 s20, 1
	s_addc_u32 s79, s2, s3
	s_mov_b32 s21, 0
	s_movk_i32 s19, 0x800
	v_add_u32_e32 v190, v152, v189
	s_mov_b32 s36, 0
	v_mov_b32_e32 v15, v14
	v_mov_b32_e32 v16, v14
	v_mov_b32_e32 v17, v14
	v_mov_b32_e32 v18, v14
	v_mov_b32_e32 v19, v14
	v_mov_b32_e32 v20, v14
	v_mov_b32_e32 v21, v14
	v_add_u32_e32 v241, v156, v163
	v_add_u32_e32 v200, v146, v145
	v_sub_u32_e32 v242, v164, v143
	v_mad_u32_u24 v242, v145, 5, v242
	v_add_u32_e32 v242, 0x18d00, v242
	v_mul_u32_u24_e32 v243, 5, v145
	v_sub_u32_e32 v243, v143, v243
	v_mul_i32_i24_e32 v243, 0x47, v243
	v_ashrrev_i32_e32 v243, 1, v243
	v_add_u32_e32 v243, v181, v243
	v_add_u32_e32 v192, v144, v145
	v_add_u32_e32 v199, v150, v145
	s_branch .LBB0_395

.Lsx0_a:
	s_and_saveexec_b64 s[2:3], s[54:55]
	s_cbranch_execz .Lsx0_c
	s_cmp_lg_u32 s21, 0
	s_cbranch_scc0 .Lsx0_c
	s_waitcnt lgkmcnt(0)
	v_cvt_pk_bf16_f32 v240, v236, v237
	global_store_dword v[238:239], v240, off

.Lpq0_end:
	s_waitcnt lgkmcnt(0)
	s_barrier
	ds_read_b128 v[48:51], v180
	ds_read_b128 v[52:55], v241 offset:62976
	ds_read_b128 v[56:59], v241 offset:64256
	ds_read_b128 v[88:91], v242
	ds_read_b128 v[92:95], v242 offset:64
	s_and_b64 s[98:99], s[56:57], exec
	s_cbranch_scc0 .Lcp0
	s_cmp_gt_u32 s36, 62
	s_cbranch_scc1 .Lcp0
	s_cmp_eq_u32 s36, 0
	s_cbranch_scc1 .Lvw0
	s_waitcnt vmcnt(14)
	s_branch .Lvx0

.Lcp0:
	s_waitcnt lgkmcnt(2)
	v_mfma_f32_16x16x32_bf16 v[14:17], v[52:55], v[48:51], v[14:17]
	v_mfma_f32_16x16x32_bf16 v[18:21], v[56:59], v[48:51], v[18:21]
	s_waitcnt lgkmcnt(0)
	s_and_saveexec_b64 s[2:3], s[56:57]
	s_cbranch_execz .Lsy0_r1
	ds_read_b128 v[62:65], v175
	ds_read_b128 v[66:69], v200

.Lsy0_r2:
	s_or_b64 exec, exec, s[2:3]
	s_nop 3
	v_pk_mul_f32 v[14:15], v[14:15], v[88:89]
	v_pk_mul_f32 v[16:17], v[16:17], v[90:91]
	v_pk_mul_f32 v[18:19], v[18:19], v[92:93]
	v_pk_mul_f32 v[20:21], v[20:21], v[94:95]
	v_cvt_pk_bf16_f32 v116, v14, v15
	v_cvt_pk_bf16_f32 v117, v16, v17
	v_cvt_pk_bf16_f32 v118, v18, v19
	v_cvt_pk_bf16_f32 v119, v20, v21
	ds_write_b64 v243, v[116:117]
	ds_write_b64 v243, v[118:119] offset:32
	s_and_saveexec_b64 s[2:3], s[56:57]
	s_cbranch_execz .Lsy0_m1
	s_waitcnt lgkmcnt(2)
	v_mfma_f32_16x16x32_bf16 v[22:25], v[62:65], v[66:69], v[22:25]

.Lpq1_end:
	s_waitcnt lgkmcnt(0)
	s_barrier
	s_and_b64 s[24:25], s[46:47], s[2:3]
	ds_read_b128 v[48:51], v180 offset:5120
	ds_read_b128 v[52:55], v170 offset:5120
	ds_read_b128 v[56:59], v170 offset:6400
	ds_read_b128 v[88:91], v242 offset:256
	ds_read_b128 v[92:95], v242 offset:320
	s_and_b64 s[98:99], s[56:57], exec
	s_cbranch_scc0 .Lcp1
	s_cmp_gt_u32 s36, 62
	s_cbranch_scc1 .Lcp1
	s_cmp_eq_u32 s36, 0
	s_cbranch_scc1 .Lvw1
	s_cmp_gt_u32 s36, 61
	s_cbranch_scc1 .Lvw1
	s_waitcnt vmcnt(14)
	s_branch .Lvx1

.Lcp1:
	s_waitcnt lgkmcnt(2)
	v_mfma_f32_16x16x32_bf16 v[14:17], v[52:55], v[48:51], v[14:17]
	v_mfma_f32_16x16x32_bf16 v[18:21], v[56:59], v[48:51], v[18:21]
	s_waitcnt lgkmcnt(0)
	s_and_saveexec_b64 s[74:75], s[56:57]
	s_cbranch_execz .Lsy1_r1
	ds_read_b128 v[62:65], v175 offset:5120
	ds_read_b128 v[66:69], v200 offset:1280

.Lsy1_r2:
	s_or_b64 exec, exec, s[74:75]
	s_nop 3
	v_pk_mul_f32 v[14:15], v[14:15], v[88:89]
	v_pk_mul_f32 v[16:17], v[16:17], v[90:91]
	v_pk_mul_f32 v[18:19], v[18:19], v[92:93]
	v_pk_mul_f32 v[20:21], v[20:21], v[94:95]
	v_cvt_pk_bf16_f32 v116, v14, v15
	v_cvt_pk_bf16_f32 v117, v16, v17
	v_cvt_pk_bf16_f32 v118, v18, v19
	v_cvt_pk_bf16_f32 v119, v20, v21
	ds_write_b64 v243, v[116:117]
	ds_write_b64 v243, v[118:119] offset:32
	s_and_saveexec_b64 s[74:75], s[56:57]
	s_cbranch_execz .Lsy1_m1
	s_waitcnt lgkmcnt(2)
	v_mfma_f32_16x16x32_bf16 v[22:25], v[62:65], v[66:69], v[22:25]
